# attention: row-max tree of unmasked tiles interleaved into the P.V MFMA gaps (on top of the LDS-DMA K/V loop)
# speedup vs baseline: 1.0691x; 1.0020x over previous
.Lat_od_nov:
	s_add_i32 m0, s32, 0x8000
	v_xor_b32_e32 v229, 64, v219
	global_load_lds_dwordx4 v219, s[98:99]
	s_add_i32 m0, s32, 0x8400
	v_add_u32_e32 v229, 0x400, v229
	global_load_lds_dwordx4 v229, s[98:99]
	s_sub_u32 s98, s98, 0x4000
	s_subb_u32 s99, s99, 0
	s_cmp_le_i32 s6, s1
	s_cbranch_scc0 .Lat_odd_orig
	s_cmp_gt_i32 s38, s8
	s_cbranch_scc0 .Lat_odd_orig
	ds_read_b64_tr_b16 v[188:189], v209 offset:0
	ds_read_b64_tr_b16 v[190:191], v209 offset:0x800
	ds_read_b64_tr_b16 v[192:193], v209 offset:0x1000
	ds_read_b64_tr_b16 v[194:195], v209 offset:0x1800
	ds_read_b64_tr_b16 v[234:235], v209 offset:0x2000
	ds_read_b64_tr_b16 v[236:237], v209 offset:0x2800
	ds_read_b64_tr_b16 v[238:239], v209 offset:0x3000
	ds_read_b64_tr_b16 v[240:241], v209 offset:0x3800
	s_nop 0
	s_waitcnt lgkmcnt(6)
	v_mfma_f32_32x32x16_bf16 v[66:81], v[178:181], v[188:191], v[66:81]
	ds_read_b64_tr_b16 v[188:189], v209 offset:0x200
	ds_read_b64_tr_b16 v[190:191], v209 offset:0xa00
	s_waitcnt lgkmcnt(6)
	v_mfma_f32_32x32x16_bf16 v[66:81], v[184:187], v[192:195], v[66:81]
	v_max_f32_e32 v250, v51, v51
	v_max_f32_e32 v251, v50, v50
	v_max_f32_e32 v250, v251, v250
	ds_read_b64_tr_b16 v[192:193], v209 offset:0x1200
	ds_read_b64_tr_b16 v[194:195], v209 offset:0x1a00
	s_waitcnt lgkmcnt(6)
	v_mfma_f32_32x32x16_bf16 v[66:81], v[230:233], v[234:237], v[66:81]
	v_max3_f32 v250, v250, v52, v53
	v_max3_f32 v250, v250, v54, v55
	v_max3_f32 v250, v250, v56, v57
	ds_read_b64_tr_b16 v[234:235], v209 offset:0x2200
	ds_read_b64_tr_b16 v[236:237], v209 offset:0x2a00
	ds_read_b64_tr_b16 v[246:247], v209 offset:0x3200
	ds_read_b64_tr_b16 v[248:249], v209 offset:0x3a00
	s_waitcnt lgkmcnt(8)
	v_mfma_f32_32x32x16_bf16 v[66:81], v[242:245], v[238:241], v[66:81]
	v_max3_f32 v250, v250, v58, v59
	v_max3_f32 v250, v250, v60, v61
	v_max3_f32 v250, v250, v62, v63
	s_waitcnt lgkmcnt(6)
	v_mfma_f32_32x32x16_bf16 v[34:49], v[178:181], v[188:191], v[34:49]
	v_max3_f32 v250, v250, v64, v65
	v_max3_f32 v250, v250, v82, v83
	v_max3_f32 v250, v250, v84, v85
	ds_read_b64_tr_b16 v[188:189], v209 offset:0x400
	ds_read_b64_tr_b16 v[190:191], v209 offset:0xc00
	s_waitcnt lgkmcnt(6)
	v_mfma_f32_32x32x16_bf16 v[34:49], v[184:187], v[192:195], v[34:49]
	v_max3_f32 v250, v250, v86, v87
	v_max3_f32 v250, v250, v88, v89
	v_max3_f32 v250, v250, v90, v91
	ds_read_b64_tr_b16 v[192:193], v209 offset:0x1400
	ds_read_b64_tr_b16 v[194:195], v209 offset:0x1c00
	s_waitcnt lgkmcnt(6)
	v_mfma_f32_32x32x16_bf16 v[34:49], v[230:233], v[234:237], v[34:49]
	v_max3_f32 v250, v250, v92, v93
	v_max3_f32 v250, v250, v94, v95
	v_max3_f32 v250, v250, v96, v97
	ds_read_b64_tr_b16 v[234:235], v209 offset:0x2400
	ds_read_b64_tr_b16 v[236:237], v209 offset:0x2c00
	ds_read_b64_tr_b16 v[238:239], v209 offset:0x3400
	ds_read_b64_tr_b16 v[240:241], v209 offset:0x3c00
	s_waitcnt lgkmcnt(8)
	v_mfma_f32_32x32x16_bf16 v[34:49], v[242:245], v[246:249], v[34:49]
	v_mov_b32_e32 v251, v250
	s_nop 1
	v_permlane32_swap_b32_e32 v250, v251
	s_waitcnt lgkmcnt(6)
	v_mfma_f32_32x32x16_bf16 v[18:33], v[178:181], v[188:191], v[18:33]
	v_max_f32_e32 v251, v251, v251
	v_max_f32_e32 v250, v250, v250
	v_max_f32_e32 v250, v250, v251
	ds_read_b64_tr_b16 v[188:189], v209 offset:0x600
	ds_read_b64_tr_b16 v[190:191], v209 offset:0xe00
	s_waitcnt lgkmcnt(6)
	v_mfma_f32_32x32x16_bf16 v[18:33], v[184:187], v[192:195], v[18:33]
	v_max_f32_e32 v253, v182, v182
	v_sub_f32_e32 v251, v250, v182
	v_max_f32_e32 v250, v253, v250
	ds_read_b64_tr_b16 v[192:193], v209 offset:0x1600
	ds_read_b64_tr_b16 v[194:195], v209 offset:0x1e00
	s_waitcnt lgkmcnt(6)
	v_mfma_f32_32x32x16_bf16 v[18:33], v[230:233], v[234:237], v[18:33]
	v_sub_f32_e32 v253, v182, v250
	v_mul_f32_e32 v253, 0x3e0293ee, v253
	v_mul_f32_e32 v251, 0x3db504f3, v251
	ds_read_b64_tr_b16 v[234:235], v209 offset:0x2600
	ds_read_b64_tr_b16 v[236:237], v209 offset:0x2e00
	ds_read_b64_tr_b16 v[246:247], v209 offset:0x3600
	ds_read_b64_tr_b16 v[248:249], v209 offset:0x3e00
	s_waitcnt lgkmcnt(8)
	v_mfma_f32_32x32x16_bf16 v[18:33], v[242:245], v[238:241], v[18:33]
	v_exp_f32_e32 v253, v253
	v_cmp_ge_f32_e32 vcc, s69, v251
	s_cmp_eq_u64 vcc, exec
	s_waitcnt lgkmcnt(6)
	v_mfma_f32_32x32x16_bf16 v[2:17], v[178:181], v[188:191], v[2:17]
	s_cselect_b64 s[6:7], -1, 0
	s_waitcnt lgkmcnt(4)
	v_mfma_f32_32x32x16_bf16 v[2:17], v[184:187], v[192:195], v[2:17]
	s_waitcnt lgkmcnt(2)
	v_mfma_f32_32x32x16_bf16 v[2:17], v[230:233], v[234:237], v[2:17]
	s_waitcnt lgkmcnt(0)
	v_mfma_f32_32x32x16_bf16 v[2:17], v[242:245], v[246:249], v[2:17]
	v_mov_b32_e32 v178, v250
	v_mov_b32_e32 v180, v253
	s_branch .Lat_odd_post
.Lat_odd_orig:
	ds_read_b64_tr_b16 v[188:189], v209 offset:0
	ds_read_b64_tr_b16 v[190:191], v209 offset:0x800
	ds_read_b64_tr_b16 v[192:193], v209 offset:0x1000
	ds_read_b64_tr_b16 v[194:195], v209 offset:0x1800
	ds_read_b64_tr_b16 v[234:235], v209 offset:0x2000
	ds_read_b64_tr_b16 v[236:237], v209 offset:0x2800
	ds_read_b64_tr_b16 v[238:239], v209 offset:0x3000
	ds_read_b64_tr_b16 v[240:241], v209 offset:0x3800
	s_nop 0
	s_waitcnt lgkmcnt(6)
	v_mfma_f32_32x32x16_bf16 v[66:81], v[178:181], v[188:191], v[66:81]
	ds_read_b64_tr_b16 v[188:189], v209 offset:0x200
	ds_read_b64_tr_b16 v[190:191], v209 offset:0xa00
	s_waitcnt lgkmcnt(6)
	v_mfma_f32_32x32x16_bf16 v[66:81], v[184:187], v[192:195], v[66:81]
	ds_read_b64_tr_b16 v[192:193], v209 offset:0x1200
	ds_read_b64_tr_b16 v[194:195], v209 offset:0x1a00
	s_waitcnt lgkmcnt(6)
	v_mfma_f32_32x32x16_bf16 v[66:81], v[230:233], v[234:237], v[66:81]
	ds_read_b64_tr_b16 v[234:235], v209 offset:0x2200
	ds_read_b64_tr_b16 v[236:237], v209 offset:0x2a00
	ds_read_b64_tr_b16 v[246:247], v209 offset:0x3200
	ds_read_b64_tr_b16 v[248:249], v209 offset:0x3a00
	s_waitcnt lgkmcnt(8)
	v_mfma_f32_32x32x16_bf16 v[66:81], v[242:245], v[238:241], v[66:81]
	s_waitcnt lgkmcnt(6)
	v_mfma_f32_32x32x16_bf16 v[34:49], v[178:181], v[188:191], v[34:49]
	ds_read_b64_tr_b16 v[188:189], v209 offset:0x400
	ds_read_b64_tr_b16 v[190:191], v209 offset:0xc00
	s_waitcnt lgkmcnt(6)
	v_mfma_f32_32x32x16_bf16 v[34:49], v[184:187], v[192:195], v[34:49]
	ds_read_b64_tr_b16 v[192:193], v209 offset:0x1400
	ds_read_b64_tr_b16 v[194:195], v209 offset:0x1c00
	s_waitcnt lgkmcnt(6)
	v_mfma_f32_32x32x16_bf16 v[34:49], v[230:233], v[234:237], v[34:49]
	ds_read_b64_tr_b16 v[234:235], v209 offset:0x2400
	ds_read_b64_tr_b16 v[236:237], v209 offset:0x2c00
	ds_read_b64_tr_b16 v[238:239], v209 offset:0x3400
	ds_read_b64_tr_b16 v[240:241], v209 offset:0x3c00
	s_waitcnt lgkmcnt(8)
	v_mfma_f32_32x32x16_bf16 v[34:49], v[242:245], v[246:249], v[34:49]
	s_waitcnt lgkmcnt(6)
	v_mfma_f32_32x32x16_bf16 v[18:33], v[178:181], v[188:191], v[18:33]
	ds_read_b64_tr_b16 v[188:189], v209 offset:0x600
	ds_read_b64_tr_b16 v[190:191], v209 offset:0xe00
	s_waitcnt lgkmcnt(6)
	v_mfma_f32_32x32x16_bf16 v[18:33], v[184:187], v[192:195], v[18:33]
	ds_read_b64_tr_b16 v[192:193], v209 offset:0x1600
	ds_read_b64_tr_b16 v[194:195], v209 offset:0x1e00
	s_waitcnt lgkmcnt(6)
	v_mfma_f32_32x32x16_bf16 v[18:33], v[230:233], v[234:237], v[18:33]
	ds_read_b64_tr_b16 v[234:235], v209 offset:0x2600
	ds_read_b64_tr_b16 v[236:237], v209 offset:0x2e00
	ds_read_b64_tr_b16 v[246:247], v209 offset:0x3600
	ds_read_b64_tr_b16 v[248:249], v209 offset:0x3e00
	s_waitcnt lgkmcnt(8)
	v_mfma_f32_32x32x16_bf16 v[18:33], v[242:245], v[238:241], v[18:33]
	s_waitcnt lgkmcnt(6)
	v_mfma_f32_32x32x16_bf16 v[2:17], v[178:181], v[188:191], v[2:17]
	s_cmp_le_i32 s6, s1
	s_cselect_b64 s[6:7], -1, 0
	s_cmp_gt_i32 s38, s8
	s_cselect_b64 s[54:55], -1, 0
	s_and_b64 s[6:7], s[6:7], s[54:55]
	s_and_b64 vcc, exec, s[6:7]
	s_waitcnt lgkmcnt(4)
	v_mfma_f32_32x32x16_bf16 v[2:17], v[184:187], v[192:195], v[2:17]
	s_waitcnt lgkmcnt(2)
	v_mfma_f32_32x32x16_bf16 v[2:17], v[230:233], v[234:237], v[2:17]
	s_waitcnt lgkmcnt(0)
	v_mfma_f32_32x32x16_bf16 v[2:17], v[242:245], v[246:249], v[2:17]
	s_cbranch_vccnz .LBB0_391
	v_subrev_u32_e32 v178, 64, v222
	v_cmp_gt_u32_e32 vcc, s11, v178
	v_add_u32_e32 v178, 0xffffefa0, v222
	s_nop 0
	v_cndmask_b32_e32 v50, v202, v50, vcc
	v_cmp_lt_u32_e32 vcc, s68, v178
	v_add_u32_e32 v178, 0xffffefbf, v222
	s_nop 0
	v_cndmask_b32_e32 v82, v202, v82, vcc
	v_cmp_lt_u32_e32 vcc, s68, v178
	v_add_u32_e32 v178, 0xffffef9f, v222
	s_nop 0
	v_cndmask_b32_e32 v51, v202, v51, vcc
	v_cmp_lt_u32_e32 vcc, s68, v178
	v_add_u32_e32 v178, 0xffffefbe, v222
	s_nop 0
	v_cndmask_b32_e32 v83, v202, v83, vcc
	v_cmp_lt_u32_e32 vcc, s68, v178
	v_add_u32_e32 v178, 0xffffef9e, v222
	s_nop 0
	v_cndmask_b32_e32 v52, v202, v52, vcc
	v_cmp_lt_u32_e32 vcc, s68, v178
	v_add_u32_e32 v178, 0xffffefbd, v222
	s_nop 0
	v_cndmask_b32_e32 v84, v202, v84, vcc
	v_cmp_lt_u32_e32 vcc, s68, v178
	v_add_u32_e32 v178, 0xffffef9d, v222
	s_nop 0
	v_cndmask_b32_e32 v53, v202, v53, vcc
	v_cmp_lt_u32_e32 vcc, s68, v178
	v_add_u32_e32 v178, 0xffffefb8, v222
	s_nop 0
	v_cndmask_b32_e32 v85, v202, v85, vcc
	v_cmp_lt_u32_e32 vcc, s68, v178
	v_add_u32_e32 v178, 0xffffef98, v222
	s_nop 0
	v_cndmask_b32_e32 v54, v202, v54, vcc
	v_cmp_lt_u32_e32 vcc, s68, v178
	v_add_u32_e32 v178, 0xffffefb7, v222
	s_nop 0
	v_cndmask_b32_e32 v86, v202, v86, vcc
	v_cmp_lt_u32_e32 vcc, s68, v178
	v_add_u32_e32 v178, 0xffffef97, v222
	s_nop 0
	v_cndmask_b32_e32 v55, v202, v55, vcc
	v_cmp_lt_u32_e32 vcc, s68, v178
	v_add_u32_e32 v178, 0xffffefb6, v222
	s_nop 0
	v_cndmask_b32_e32 v87, v202, v87, vcc
	v_cmp_lt_u32_e32 vcc, s68, v178
	v_add_u32_e32 v178, 0xffffef96, v222
	s_nop 0
	v_cndmask_b32_e32 v56, v202, v56, vcc
	v_cmp_lt_u32_e32 vcc, s68, v178
	v_add_u32_e32 v178, 0xffffefb5, v222
	s_nop 0
	v_cndmask_b32_e32 v88, v202, v88, vcc
	v_cmp_lt_u32_e32 vcc, s68, v178
	v_add_u32_e32 v178, 0xffffef95, v222
	s_nop 0
	v_cndmask_b32_e32 v57, v202, v57, vcc
	v_cmp_lt_u32_e32 vcc, s68, v178
	v_add_u32_e32 v178, 0xffffefb0, v222
	s_nop 0
	v_cndmask_b32_e32 v89, v202, v89, vcc
	v_cmp_lt_u32_e32 vcc, s68, v178
	v_add_u32_e32 v178, 0xffffef90, v222
	s_nop 0
	v_cndmask_b32_e32 v58, v202, v58, vcc
	v_cmp_lt_u32_e32 vcc, s68, v178
	v_add_u32_e32 v178, 0xffffefaf, v222
	s_nop 0
	v_cndmask_b32_e32 v90, v202, v90, vcc
	v_cmp_lt_u32_e32 vcc, s68, v178
	v_add_u32_e32 v178, 0xffffef8f, v222
	s_nop 0
	v_cndmask_b32_e32 v59, v202, v59, vcc
	v_cmp_lt_u32_e32 vcc, s68, v178
	v_add_u32_e32 v178, 0xffffefae, v222
	s_nop 0
	v_cndmask_b32_e32 v91, v202, v91, vcc
	v_cmp_lt_u32_e32 vcc, s68, v178
	v_add_u32_e32 v178, 0xffffef8e, v222
	s_nop 0
	v_cndmask_b32_e32 v60, v202, v60, vcc
	v_cmp_lt_u32_e32 vcc, s68, v178
	v_add_u32_e32 v178, 0xffffefad, v222
	s_nop 0
	v_cndmask_b32_e32 v92, v202, v92, vcc
	v_cmp_lt_u32_e32 vcc, s68, v178
	v_add_u32_e32 v178, 0xffffef8d, v222
	s_nop 0
	v_cndmask_b32_e32 v61, v202, v61, vcc
	v_cmp_lt_u32_e32 vcc, s68, v178
	v_add_u32_e32 v178, 0xffffefa8, v222
	s_nop 0
	v_cndmask_b32_e32 v93, v202, v93, vcc
	v_cmp_lt_u32_e32 vcc, s68, v178
	v_add_u32_e32 v178, 0xffffef88, v222
	s_nop 0
	v_cndmask_b32_e32 v62, v202, v62, vcc
	v_cmp_lt_u32_e32 vcc, s68, v178
	v_add_u32_e32 v178, 0xffffefa7, v222
	s_nop 0
	v_cndmask_b32_e32 v94, v202, v94, vcc
	v_cmp_lt_u32_e32 vcc, s68, v178
	v_add_u32_e32 v178, 0xffffef87, v222
	s_nop 0
	v_cndmask_b32_e32 v63, v202, v63, vcc
	v_cmp_lt_u32_e32 vcc, s68, v178
	v_add_u32_e32 v178, 0xffffefa6, v222
	s_nop 0
	v_cndmask_b32_e32 v95, v202, v95, vcc
	v_cmp_lt_u32_e32 vcc, s68, v178
	v_add_u32_e32 v178, 0xffffef86, v222
	s_nop 0
	v_cndmask_b32_e32 v64, v202, v64, vcc
	v_cmp_lt_u32_e32 vcc, s68, v178
	v_add_u32_e32 v178, 0xffffefa5, v222
	s_nop 0
	v_cndmask_b32_e32 v96, v202, v96, vcc
	v_cmp_lt_u32_e32 vcc, s68, v178
	v_add_u32_e32 v178, 0xffffef85, v222
	s_nop 0
	v_cndmask_b32_e32 v65, v202, v65, vcc
	v_cmp_lt_u32_e32 vcc, s68, v178
	s_nop 1
	v_cndmask_b32_e32 v97, v202, v97, vcc

.Lat_odd_post:
	v_cndmask_b32_e64 v225, v180, 1.0, s[6:7]
	v_cmp_gt_f32_e32 vcc, 1.0, v225
	s_cbranch_vccz .LBB0_395
	s_and_saveexec_b64 s[54:55], s[4:5]
	ds_write_b32 v208, v225 offset:128
	s_or_b64 exec, exec, s[54:55]
	s_waitcnt lgkmcnt(0)
	ds_read_b128 v[184:187], v207 offset:224
	ds_read_b128 v[188:191], v207 offset:192
	ds_read_b128 v[192:195], v207 offset:160
	ds_read_b128 v[230:233], v207 offset:128
	s_waitcnt lgkmcnt(3)
	v_pk_mul_f32 v[80:81], v[80:81], v[186:187]
	s_waitcnt lgkmcnt(2)
	v_pk_mul_f32 v[76:77], v[76:77], v[190:191]
	s_waitcnt lgkmcnt(1)
	v_pk_mul_f32 v[72:73], v[72:73], v[194:195]
	s_waitcnt lgkmcnt(0)
	v_pk_mul_f32 v[68:69], v[68:69], v[232:233]
	v_pk_mul_f32 v[78:79], v[78:79], v[184:185]
	v_pk_mul_f32 v[74:75], v[74:75], v[188:189]
	v_pk_mul_f32 v[70:71], v[70:71], v[192:193]
	v_pk_mul_f32 v[66:67], v[66:67], v[230:231]
	v_pk_mul_f32 v[48:49], v[48:49], v[186:187]
	v_pk_mul_f32 v[44:45], v[44:45], v[190:191]
	v_pk_mul_f32 v[40:41], v[40:41], v[194:195]
	v_pk_mul_f32 v[36:37], v[36:37], v[232:233]
	v_pk_mul_f32 v[46:47], v[46:47], v[184:185]
	v_pk_mul_f32 v[42:43], v[42:43], v[188:189]
	v_pk_mul_f32 v[38:39], v[38:39], v[192:193]
	v_pk_mul_f32 v[34:35], v[34:35], v[230:231]
	v_pk_mul_f32 v[32:33], v[32:33], v[186:187]
	v_pk_mul_f32 v[28:29], v[28:29], v[190:191]
	v_pk_mul_f32 v[24:25], v[24:25], v[194:195]
	v_pk_mul_f32 v[20:21], v[20:21], v[232:233]
	v_pk_mul_f32 v[30:31], v[30:31], v[184:185]
	v_pk_mul_f32 v[26:27], v[26:27], v[188:189]
	v_pk_mul_f32 v[22:23], v[22:23], v[192:193]
	v_pk_mul_f32 v[18:19], v[18:19], v[230:231]
	v_pk_mul_f32 v[16:17], v[16:17], v[186:187]
	v_pk_mul_f32 v[12:13], v[12:13], v[190:191]
	v_pk_mul_f32 v[8:9], v[8:9], v[194:195]
	v_pk_mul_f32 v[4:5], v[4:5], v[232:233]
	v_pk_mul_f32 v[14:15], v[14:15], v[184:185]
	v_pk_mul_f32 v[10:11], v[10:11], v[188:189]
	v_pk_mul_f32 v[6:7], v[6:7], v[192:193]
	v_pk_mul_f32 v[2:3], v[2:3], v[230:231]

.LBB0_397:
	s_add_i32 s6, s38, -1
	s_cmp_le_i32 s6, s1
	s_cbranch_scc0 .Lat_even_orig
	s_sub_i32 s39, s38, 64
	s_cmp_gt_i32 s39, s8
	s_cbranch_scc0 .Lat_even_orig
	ds_read_b64_tr_b16 v[230:231], v209 offset:0x4000
	ds_read_b64_tr_b16 v[232:233], v209 offset:0x4800
	ds_read_b64_tr_b16 v[234:235], v209 offset:0x5000
	ds_read_b64_tr_b16 v[236:237], v209 offset:0x5800
	ds_read_b64_tr_b16 v[238:239], v209 offset:0x6000
	ds_read_b64_tr_b16 v[240:241], v209 offset:0x6800
	ds_read_b64_tr_b16 v[242:243], v209 offset:0x7000
	ds_read_b64_tr_b16 v[244:245], v209 offset:0x7800
	s_add_i32 s6, s38, -1
	s_sub_i32 s39, s38, 64
	s_waitcnt lgkmcnt(6)
	v_mfma_f32_32x32x16_bf16 v[66:81], v[178:181], v[230:233], v[66:81]
	ds_read_b64_tr_b16 v[230:231], v209 offset:0x4200
	ds_read_b64_tr_b16 v[232:233], v209 offset:0x4a00
	s_waitcnt lgkmcnt(6)
	v_mfma_f32_32x32x16_bf16 v[66:81], v[182:185], v[234:237], v[66:81]
	v_max_f32_e32 v250, v115, v115
	v_max_f32_e32 v251, v114, v114
	v_max_f32_e32 v250, v251, v250
	ds_read_b64_tr_b16 v[234:235], v209 offset:0x5200
	ds_read_b64_tr_b16 v[236:237], v209 offset:0x5a00
	s_waitcnt lgkmcnt(6)
	v_mfma_f32_32x32x16_bf16 v[66:81], v[186:189], v[238:241], v[66:81]
	v_max3_f32 v250, v250, v116, v117
	v_max3_f32 v250, v250, v118, v119
	v_max3_f32 v250, v250, v120, v121
	ds_read_b64_tr_b16 v[238:239], v209 offset:0x6200
	ds_read_b64_tr_b16 v[240:241], v209 offset:0x6a00
	ds_read_b64_tr_b16 v[246:247], v209 offset:0x7200
	ds_read_b64_tr_b16 v[248:249], v209 offset:0x7a00
	s_waitcnt lgkmcnt(8)
	v_mfma_f32_32x32x16_bf16 v[66:81], v[190:193], v[242:245], v[66:81]
	v_max3_f32 v250, v250, v122, v123
	v_max3_f32 v250, v250, v124, v125
	v_max3_f32 v250, v250, v126, v127
	s_waitcnt lgkmcnt(6)
	v_mfma_f32_32x32x16_bf16 v[34:49], v[178:181], v[230:233], v[34:49]
	v_max3_f32 v250, v250, v128, v129
	v_max3_f32 v250, v250, v98, v99
	v_max3_f32 v250, v250, v100, v101
	ds_read_b64_tr_b16 v[230:231], v209 offset:0x4400
	ds_read_b64_tr_b16 v[232:233], v209 offset:0x4c00
	s_waitcnt lgkmcnt(6)
	v_mfma_f32_32x32x16_bf16 v[34:49], v[182:185], v[234:237], v[34:49]
	v_max3_f32 v250, v250, v102, v103
	v_max3_f32 v250, v250, v104, v105
	v_max3_f32 v250, v250, v106, v107
	ds_read_b64_tr_b16 v[234:235], v209 offset:0x5400
	ds_read_b64_tr_b16 v[236:237], v209 offset:0x5c00
	s_waitcnt lgkmcnt(6)
	v_mfma_f32_32x32x16_bf16 v[34:49], v[186:189], v[238:241], v[34:49]
	v_max3_f32 v250, v250, v108, v109
	v_max3_f32 v250, v250, v110, v111
	v_max3_f32 v250, v250, v112, v113
	ds_read_b64_tr_b16 v[238:239], v209 offset:0x6400
	ds_read_b64_tr_b16 v[240:241], v209 offset:0x6c00
	ds_read_b64_tr_b16 v[242:243], v209 offset:0x7400
	ds_read_b64_tr_b16 v[244:245], v209 offset:0x7c00
	s_waitcnt lgkmcnt(8)
	v_mfma_f32_32x32x16_bf16 v[34:49], v[190:193], v[246:249], v[34:49]
	v_mov_b32_e32 v251, v250
	s_nop 1
	v_permlane32_swap_b32_e32 v250, v251
	s_waitcnt lgkmcnt(6)
	v_mfma_f32_32x32x16_bf16 v[18:33], v[178:181], v[230:233], v[18:33]
	v_max_f32_e32 v251, v251, v251
	v_max_f32_e32 v250, v250, v250
	v_max_f32_e32 v250, v250, v251
	ds_read_b64_tr_b16 v[230:231], v209 offset:0x4600
	ds_read_b64_tr_b16 v[232:233], v209 offset:0x4e00
	s_waitcnt lgkmcnt(6)
	v_mfma_f32_32x32x16_bf16 v[18:33], v[182:185], v[234:237], v[18:33]
	v_sub_f32_e32 v251, v250, v226
	v_mul_f32_e32 v251, 0x3db504f3, v251
	v_cmp_ge_f32_e32 vcc, s69, v251
	ds_read_b64_tr_b16 v[234:235], v209 offset:0x5600
	ds_read_b64_tr_b16 v[236:237], v209 offset:0x5e00
	s_waitcnt lgkmcnt(6)
	v_mfma_f32_32x32x16_bf16 v[18:33], v[186:189], v[238:241], v[18:33]
	s_cmp_eq_u64 vcc, exec
	s_cselect_b64 s[6:7], -1, 0
	s_andn2_b64 vcc, exec, s[54:55]
	ds_read_b64_tr_b16 v[238:239], v209 offset:0x6600
	ds_read_b64_tr_b16 v[240:241], v209 offset:0x6e00
	ds_read_b64_tr_b16 v[246:247], v209 offset:0x7600
	ds_read_b64_tr_b16 v[248:249], v209 offset:0x7e00
	s_waitcnt lgkmcnt(8)
	v_mfma_f32_32x32x16_bf16 v[18:33], v[190:193], v[242:245], v[18:33]
	s_waitcnt lgkmcnt(6)
	v_mfma_f32_32x32x16_bf16 v[2:17], v[178:181], v[230:233], v[2:17]
	s_waitcnt lgkmcnt(4)
	v_mfma_f32_32x32x16_bf16 v[2:17], v[182:185], v[234:237], v[2:17]
	s_waitcnt lgkmcnt(2)
	v_mfma_f32_32x32x16_bf16 v[2:17], v[186:189], v[238:241], v[2:17]
	s_waitcnt lgkmcnt(0)
	v_mfma_f32_32x32x16_bf16 v[2:17], v[190:193], v[246:249], v[2:17]
	v_mov_b32_e32 v178, v250
	s_branch .Lat_even_post

.Lat_even_post:
.LBB0_401:
	v_max_f32_e32 v162, v226, v226
	v_max_f32_e32 v162, v162, v178
	v_sub_f32_e32 v163, v226, v162
	v_mul_f32_e32 v163, 0x3e0293ee, v163
	v_exp_f32_e32 v163, v163
	s_nop 0
	v_cndmask_b32_e64 v178, v163, 1.0, s[6:7]
	v_cmp_gt_f32_e32 vcc, 1.0, v178
	s_cbranch_vccz .LBB0_405
	s_and_saveexec_b64 s[54:55], s[4:5]
	ds_write_b32 v208, v178 offset:128
	s_or_b64 exec, exec, s[54:55]
	s_waitcnt lgkmcnt(0)
	ds_read_b128 v[164:167], v207 offset:224
	ds_read_b128 v[168:171], v207 offset:192
	ds_read_b128 v[172:175], v207 offset:160
	ds_read_b128 v[180:183], v207 offset:128
	s_waitcnt lgkmcnt(3)
	v_pk_mul_f32 v[80:81], v[80:81], v[166:167]
	s_waitcnt lgkmcnt(2)
	v_pk_mul_f32 v[76:77], v[76:77], v[170:171]
	s_waitcnt lgkmcnt(1)
	v_pk_mul_f32 v[72:73], v[72:73], v[174:175]
	s_waitcnt lgkmcnt(0)
	v_pk_mul_f32 v[68:69], v[68:69], v[182:183]
	v_pk_mul_f32 v[78:79], v[78:79], v[164:165]
	v_pk_mul_f32 v[74:75], v[74:75], v[168:169]
	v_pk_mul_f32 v[70:71], v[70:71], v[172:173]
	v_pk_mul_f32 v[66:67], v[66:67], v[180:181]
	v_pk_mul_f32 v[48:49], v[48:49], v[166:167]
	v_pk_mul_f32 v[44:45], v[44:45], v[170:171]
	v_pk_mul_f32 v[40:41], v[40:41], v[174:175]
	v_pk_mul_f32 v[36:37], v[36:37], v[182:183]
	v_pk_mul_f32 v[46:47], v[46:47], v[164:165]
	v_pk_mul_f32 v[42:43], v[42:43], v[168:169]
	v_pk_mul_f32 v[38:39], v[38:39], v[172:173]
	v_pk_mul_f32 v[34:35], v[34:35], v[180:181]
	v_pk_mul_f32 v[32:33], v[32:33], v[166:167]
	v_pk_mul_f32 v[28:29], v[28:29], v[170:171]
	v_pk_mul_f32 v[24:25], v[24:25], v[174:175]
	v_pk_mul_f32 v[20:21], v[20:21], v[182:183]
	v_pk_mul_f32 v[30:31], v[30:31], v[164:165]
	v_pk_mul_f32 v[26:27], v[26:27], v[168:169]
	v_pk_mul_f32 v[22:23], v[22:23], v[172:173]
	v_pk_mul_f32 v[18:19], v[18:19], v[180:181]
	v_pk_mul_f32 v[16:17], v[16:17], v[166:167]
	v_pk_mul_f32 v[12:13], v[12:13], v[170:171]
	v_pk_mul_f32 v[8:9], v[8:9], v[174:175]
	v_pk_mul_f32 v[4:5], v[4:5], v[182:183]
	v_pk_mul_f32 v[14:15], v[14:15], v[164:165]
	v_pk_mul_f32 v[10:11], v[10:11], v[168:169]
	v_pk_mul_f32 v[6:7], v[6:7], v[172:173]
	v_pk_mul_f32 v[2:3], v[2:3], v[180:181]
